# diff loop: next-interval loads issued at end of interval; setprio 1 around MFMA block of waves 4-7 only
# baseline (speedup 1.0000x reference)
; template <bool DIFF>
; __device__ __forceinline__ void attn_unit(const AttnP& A, int b, int h, int qi, ldsp lds) {
;     ...
;     const bf16* Pq = A.P + (Rb + q_pp) * NP;
;     bf16x8 qf[4];
; #pragma unroll
;     for (int c = 0; c < 4; ++c) qf[c] = *(const bf16x8*)(Pq + qcol + 16 * c + 8 * hi);
;     LAS float* pref = (LAS float*)(lds + LDS_PREF);
;     u32x4 kreg[NPIECE], vreg[NPIECE]; float clreg = 0.f;
;     ...
;     int kt0 = 0;
;     if (!DIFF) {
;         LAS int* kst = (LAS int*)(lds + LDS_MISC + 64);
;         if (tid == 0) *kst = nt - 1;
;         if (w == 0) {
;             float carry = 0.f;
; #pragma unroll
;             for (int ch = 0; ch < 3; ++ch) {
;                 const int idx = ch * 64 + lane;
;                 const float v = idx < TPB ? A.cumtot[(b * TPB + idx) * 8 + h] : 0.f;
;                 float inc = v;
; #pragma unroll
;                 for (int o = 1; o < 64; o <<= 1) { const float t_ = __shfl_up(inc, o); if (lane >= o) inc += t_; }
;                 if (idx < TPB) pref[idx] = carry + inc - v;
;                 if (idx == TPB - 1) pref[TPB] = carry + inc;
;                 carry += __shfl(inc, 63);
;             }
;         }
;         __syncthreads();
;         const float q2 = __uint_as_float(A.nrm[(h) * 2]) + __uint_as_float(A.nrm[(h) * 2 + 1]), k2r = __uint_as_float(A.nrm[(8 + h) * 2]) + __uint_as_float(A.nrm[(8 + h) * 2 + 1]),
;                     k2m = (__uint_as_float(A.nrm[32 + h * 4]) + __uint_as_float(A.nrm[32 + h * 4 + 1])) + (__uint_as_float(A.nrm[32 + h * 4 + 2]) + __uint_as_float(A.nrm[32 + h * 4 + 3])), k2 = fmaxf(k2r, k2m);
;         const float thr = 2.0f * 1.03f * sqrtf(q2 * k2) + 40.0f;
;         if (tid < nt) { if (pref[qstart >> 6] - pref[tid + 1] >= -thr) atomicMin((int*)kst, tid); }
;         __syncthreads();
;         kt0 = *kst;
;     }
;     LOAD_TILE(kt0);
;     STORE_TILE(kt0 & 1);
;     __syncthreads();
;     float cq = 0.f;
;     if (!DIFF) cq = pref[q_pp >> 6] + A.cumloc[(Rb + q_pp) * 8 + h];
;     float mhat = 0.f, l_run = 0.f;
;     f32x16 negm;
; #pragma unroll
;     for (int r = 0; r < 16; ++r) negm[r] = 0.f;
;     f32x16 o[NTD];
; #pragma unroll
;     for (int t = 0; t < NTD; ++t)
; #pragma unroll
;         for (int r = 0; r < 16; ++r) o[t][r] = 0.f;
;     const int trb = (4 * hi + ((lane & 15) >> 2)) * VP + ((lane >> 4) & 1) * 32 + (lane & 3) * 8;
;     for (int kt = kt0; kt < nt; ++kt) {
.LBB0_495:
	s_and_b64 vcc, exec, s[0:1]
	s_cbranch_vccz .LBB0_439
	s_mul_hi_i32 s0, s31, 0x7e07e07f
	s_lshr_b32 s1, s0, 31
	s_ashr_i32 s51, s0, 5
	s_add_i32 s51, s51, s1
	v_mov_b32_e32 v225, v200
	s_mul_i32 s0, s51, 0x41
	s_sub_i32 s0, s31, s0
	v_readfirstlane_b32 s64, v225
	s_ashr_i32 s22, s51, 2
	s_ashr_i32 s70, s64, 8
	s_bfe_u32 s65, s64, 0x20006
	s_cmp_eq_u32 s0, 0
	s_cselect_b64 s[24:25], -1, 0
	s_lshl_b32 s1, s0, 7
	s_sub_i32 s1, s1, 64
	s_cmp_lg_u32 s0, 0
	s_cselect_b64 s[16:17], -1, 0
	s_and_b64 s[40:41], s[16:17], exec
	s_cselect_b32 s1, s1, 0
	s_lshl_b32 s23, s65, 5
	v_and_b32_e32 v6, 31, v225
	s_add_i32 s1, s23, s1
	v_or_b32_e32 v192, s1, v6
	s_lshl_b32 s23, s51, 7
	v_ashrrev_i32_e32 v193, 31, v192
	s_and_b32 s50, s23, 0x180
	s_lshl_b32 s23, s70, 6
	v_mad_i64_i32 v[2:3], s[44:45], s22, v221, v[192:193]
	s_add_i32 s40, s23, s50
	v_lshlrev_b64 v[2:3], 13, v[2:3]
	v_bfe_u32 v7, v225, 5, 1
	v_lshl_add_u64 v[190:191], s[58:59], 0, v[2:3]
	s_ashr_i32 s41, s40, 31
	v_lshl_add_u64 v[2:3], s[40:41], 1, v[190:191]
	v_lshlrev_b32_e32 v194, 4, v7
	v_mov_b32_e32 v195, v1
	s_mul_i32 s41, s22, 0x4080000
	v_ashrrev_i32_e32 v8, 4, v225
	v_lshl_add_u64 v[2:3], v[2:3], 0, v[194:195]
	s_mul_hi_i32 s40, s22, 0x4080000
	s_add_u32 s44, s58, s41
	v_ashrrev_i32_e32 v9, 31, v8
	global_load_dwordx4 v[116:119], v[2:3], off
	global_load_dwordx4 v[120:123], v[2:3], off offset:32
	global_load_dwordx4 v[124:127], v[2:3], off offset:64
	global_load_dwordx4 v[128:131], v[2:3], off offset:96
	s_addc_u32 s45, s59, s40
	v_lshlrev_b64 v[2:3], 13, v[8:9]
	v_lshl_add_u64 v[4:5], s[44:45], 0, v[2:3]
	s_lshl_b32 s34, s50, 1
	v_lshlrev_b32_e32 v0, 4, v225
	v_lshl_add_u64 v[4:5], v[4:5], 0, s[34:35]
	v_and_b32_e32 v0, 0xf0, v0
	v_lshl_add_u64 v[4:5], v[4:5], 0, v[0:1]
	global_load_dwordx4 v[132:135], v[4:5], off offset:1024
	global_load_dwordx4 v[136:139], v[4:5], off offset:2048
	v_add_u32_e32 v4, 0x200, v225
	v_ashrrev_i32_e32 v10, 4, v4
	v_ashrrev_i32_e32 v11, 31, v10
	v_lshlrev_b64 v[4:5], 13, v[10:11]
	v_lshl_add_u64 v[12:13], s[44:45], 0, v[4:5]
	v_lshl_add_u64 v[12:13], v[12:13], 0, s[34:35]
	v_lshl_add_u64 v[12:13], v[12:13], 0, v[0:1]
	global_load_dwordx4 v[140:143], v[12:13], off offset:1024
	global_load_dwordx4 v[144:147], v[12:13], off offset:2048
	s_movk_i32 s23, 0x110
	v_add_u32_e32 v195, 0, v0
	v_mul_lo_u32 v226, v8, s23
	s_movk_i32 s44, 0x140
	v_add_u32_e32 v0, v195, v226
	v_mul_lo_u32 v227, v8, s44
	v_mul_lo_u32 v228, v10, s23
	v_mul_lo_u32 v229, v10, s44
	v_lshlrev_b32_e32 v115, 2, v7
	s_cmp_lt_i32 s0, 0
	s_waitcnt vmcnt(3)
	ds_write_b128 v0, v[132:135]
	v_add_u32_e32 v0, v195, v227
	s_waitcnt vmcnt(2)
	ds_write_b128 v0, v[136:139] offset:17408
	v_add_u32_e32 v0, v195, v228
	s_waitcnt vmcnt(1)
	ds_write_b128 v0, v[140:143]
	v_add_u32_e32 v0, v195, v229
	s_waitcnt vmcnt(0)
	ds_write_b128 v0, v[144:147] offset:17408
	s_waitcnt lgkmcnt(0)
	s_barrier
	s_cbranch_scc1 .LBB0_514
	s_lshl_b32 s23, s0, 1
	s_or_b32 s71, s1, 31
	s_lshl_b32 s0, s31, 1
	s_mul_i32 s1, s51, 0x82
	s_sub_i32 s0, s0, s1
	s_or_b32 s31, s0, 1
	s_and_b32 s0, s51, 3
	s_add_i32 s72, s23, -1
	s_lshl_b32 s73, s70, 7
	s_lshl_b32 s0, s0, 8
	s_add_u32 s0, s36, s0
	v_lshrrev_b32_e32 v7, 2, v225
	s_addc_u32 s1, s37, 0
	v_and_or_b32 v7, v7, 3, v115
	s_add_u32 s0, s0, s41
	v_lshlrev_b32_e32 v0, 3, v225
	v_mul_u32_u24_e32 v231, 0x140, v7
	v_lshlrev_b32_e32 v7, 1, v225
	s_addc_u32 s1, s1, s40
	v_mov_b32_e32 v16, v1
	v_mov_b32_e32 v17, v1
	v_and_b32_e32 v232, 32, v7
	v_and_b32_e32 v233, 24, v0
	v_mul_u32_u24_e32 v234, 0x110, v6
	v_and_b32_e32 v0, 15, v225
	v_lshl_add_u64 v[196:197], s[0:1], 0, v[2:3]
	v_lshl_add_u64 v[198:199], s[0:1], 0, v[4:5]
	v_mov_b32_e32 v2, v1
	v_mov_b32_e32 v3, v1
	v_mov_b32_e32 v4, v1
	v_mov_b32_e32 v5, v1
	v_mov_b32_e32 v6, v1
	v_mov_b32_e32 v7, v1
	v_mov_b32_e32 v8, v1
	v_mov_b32_e32 v9, v1
	v_mov_b32_e32 v10, v1
	v_mov_b32_e32 v11, v1
	v_mov_b32_e32 v12, v1
	v_mov_b32_e32 v13, v1
	v_mov_b32_e32 v14, v1
	v_mov_b32_e32 v15, v1
	v_mov_b32_e32 v235, 0
	v_mov_b64_e32 v[32:33], v[16:17]
	v_mov_b64_e32 v[48:49], v[16:17]
	v_mov_b64_e32 v[64:65], v[16:17]
	v_lshlrev_b32_e32 v0, 4, v0
	s_mov_b32 s74, 0
	v_mov_b64_e32 v[30:31], v[14:15]
	v_mov_b64_e32 v[28:29], v[12:13]
	v_mov_b64_e32 v[26:27], v[10:11]
	v_mov_b64_e32 v[24:25], v[8:9]
	v_mov_b64_e32 v[22:23], v[6:7]
	v_mov_b64_e32 v[20:21], v[4:5]
	v_mov_b64_e32 v[18:19], v[2:3]
	v_mov_b64_e32 v[46:47], v[14:15]
	v_mov_b64_e32 v[44:45], v[12:13]
	v_mov_b64_e32 v[42:43], v[10:11]
	v_mov_b64_e32 v[40:41], v[8:9]
	v_mov_b64_e32 v[38:39], v[6:7]
	v_mov_b64_e32 v[36:37], v[4:5]
	v_mov_b64_e32 v[34:35], v[2:3]
	v_mov_b64_e32 v[62:63], v[14:15]
	v_mov_b64_e32 v[60:61], v[12:13]
	v_mov_b64_e32 v[58:59], v[10:11]
	v_mov_b64_e32 v[56:57], v[8:9]
	v_mov_b64_e32 v[54:55], v[6:7]
	v_mov_b64_e32 v[52:53], v[4:5]
	v_mov_b64_e32 v[50:51], v[2:3]
	v_mov_b32_e32 v230, 0
	s_mov_b32 s75, 0
	v_mov_b32_e32 v66, 0
	v_mov_b32_e32 v67, v235
	v_mov_b32_e32 v68, v235
	v_mov_b32_e32 v69, v235
	v_mov_b32_e32 v70, v235
	v_mov_b32_e32 v71, v235
	v_mov_b32_e32 v72, v235
	v_mov_b32_e32 v73, v235
	v_mov_b32_e32 v74, v235
	v_mov_b32_e32 v75, v235
	v_mov_b32_e32 v76, v235
	v_mov_b32_e32 v77, v235
	v_mov_b32_e32 v78, v235
	v_mov_b32_e32 v79, v235
	v_mov_b32_e32 v80, v235
	v_mov_b32_e32 v81, v235
	s_lshr_b32 s44, s71, 6
	s_add_i32 s44, s44, 1
	s_min_i32 s44, s44, s31
	v_add_u32_e32 v226, v195, v226
	v_add_u32_e32 v227, v195, v227
	v_add_u32_e32 v228, v195, v228
	v_add_u32_e32 v229, v195, v229
	v_add3_u32 v231, v231, v232, v233
	v_add3_u32 v234, v234, v194, s73
	v_lshl_add_u64 v[196:197], v[196:197], 0, v[0:1]
	v_lshl_add_u64 v[198:199], v[198:199], 0, v[0:1]
	v_add_co_u32_e32 v196, vcc, 0x5c00000, v196
	s_nop 1
	v_addc_co_u32_e32 v197, vcc, 0, v197, vcc
	v_add_co_u32_e32 v198, vcc, 0x5c00000, v198
	s_nop 1
	v_addc_co_u32_e32 v199, vcc, 0, v199, vcc
	v_lshl_add_u64 v[196:197], v[196:197], 0, s[26:27]
	v_lshl_add_u64 v[198:199], v[198:199], 0, s[26:27]
	global_load_dwordx4 v[132:135], v[196:197], off offset:1024
	global_load_dwordx4 v[140:143], v[198:199], off offset:1024
	s_cmp_lg_u32 s70, 0
	s_cbranch_scc1 .Ldb_top
; __device__ __forceinline__ s16x4 vtr(ldsp p) { return __builtin_bit_cast(s16x4, __builtin_amdgcn_ds_read_tr16_b64_v4i16((LAS v4i16_t*)p)); }
; template <bool DIFF>
; __device__ __forceinline__ void attn_unit(const AttnP& A, int b, int h, int qi, ldsp lds) {
;     ...
;     for (int kt = kt0; kt < nt; ++kt) {
;         if (kt + 1 < nt) LOAD_TILE(kt + 1);
;         if (64 * kt <= qmax_w) {
;             ldsp Kb = lds + (kt & 1) * STAGE; ldsp Vb = Kb + 64 * KP;
;             bf16x8 kf[8]; bf16x8 ka0, ka1, qa; f32x16 s0, s1;
;     ...
;             QK_BLOCK();
;             s16x4 vlo[8], vhi[8];
; #pragma unroll
;             for (int t = 0; t < 2; ++t)
; #pragma unroll
;                 for (int j = 0; j < 4; ++j) { vlo[t * 4 + j] = vtr(Vb + trb + (16 * j) * VP + t * 64); vhi[t * 4 + j] = vtr(Vb + trb + (16 * j + 8) * VP + t * 64); }
;     ...
; #pragma unroll
;             for (int t = 0; t < 2; ++t)
; #pragma unroll
;                 for (int j = 0; j < 4; ++j) {
;                     const bf16x8 vf = (bf16x8){vlo[t * 4 + j][0], vlo[t * 4 + j][1], vlo[t * 4 + j][2], vlo[t * 4 + j][3], vhi[t * 4 + j][0], vhi[t * 4 + j][1], vhi[t * 4 + j][2], vhi[t * 4 + j][3]};
;                     o[t] = __builtin_amdgcn_mfma_f32_32x32x16_bf16(vf, pw[j], o[t], 0, 0, 0);
;                 }
;             if (DIFF) {
; #pragma unroll
;                 for (int t = 2; t < NTD; ++t)
; #pragma unroll
;                     for (int j = 0; j < 4; ++j) { vlo[(t - 2) * 4 + j] = vtr(Vb + trb + (16 * j) * VP + t * 64); vhi[(t - 2) * 4 + j] = vtr(Vb + trb + (16 * j + 8) * VP + t * 64); }
;                 __builtin_amdgcn_sched_barrier(0);
; #pragma unroll
;                 for (int t = 2; t < NTD; ++t)
; #pragma unroll
;                     for (int j = 0; j < 4; ++j) {
;                         const int i = (t - 2) * 4 + j;
;                         const bf16x8 vf = (bf16x8){vlo[i][0], vlo[i][1], vlo[i][2], vlo[i][3], vhi[i][0], vhi[i][1], vhi[i][2], vhi[i][3]};
;                         o[t] = __builtin_amdgcn_mfma_f32_32x32x16_bf16(vf, pw[j], o[t], 0, 0, 0);
;                     }
;             }
.Lda_top:
	s_bitcmp1_b32 s75, 0
	s_cselect_b32 s45, 0x9500, 0
	s_sub_i32 s71, 0x9500, s45
	s_cmp_eq_u32 s75, 0
	s_cbranch_scc1 .Lda_first
	s_cmp_gt_i32 s75, s44
	s_cbranch_scc1 .Lda_idle
	s_cmp_eq_u32 s75, s44
	s_cbranch_scc1 .Lda_last
	v_add_u32_e32 v239, s45, v234
	v_add_u32_e32 v236, s71, v231
	ds_read_b64_tr_b16 v[148:149], v236 offset:17472
	ds_read_b64_tr_b16 v[150:151], v236 offset:20032
	ds_read_b64_tr_b16 v[152:153], v236 offset:17408
	ds_read_b64_tr_b16 v[154:155], v236 offset:19968
	ds_read_b64_tr_b16 v[156:157], v236 offset:22592
	ds_read_b64_tr_b16 v[158:159], v236 offset:25152
	ds_read_b64_tr_b16 v[160:161], v236 offset:22528
	ds_read_b64_tr_b16 v[162:163], v236 offset:25088
	ds_read_b64_tr_b16 v[164:165], v236 offset:27712
	ds_read_b64_tr_b16 v[166:167], v236 offset:30272
	ds_read_b64_tr_b16 v[168:169], v236 offset:27648
	ds_read_b64_tr_b16 v[170:171], v236 offset:30208
	ds_read_b64_tr_b16 v[172:173], v236 offset:32768
	ds_read_b64_tr_b16 v[174:175], v236 offset:35328
	ds_read_b64_tr_b16 v[176:177], v236 offset:32832
	ds_read_b64_tr_b16 v[178:179], v236 offset:35392
	s_waitcnt lgkmcnt(14)
	v_mfma_f32_32x32x16_bf16 v[34:49], v[148:151], v[98:101], v[34:49]
	ds_read_b64_tr_b16 v[90:91], v236 offset:17536
	ds_read_b64_tr_b16 v[92:93], v236 offset:20096
	s_waitcnt lgkmcnt(14)
	v_mfma_f32_32x32x16_bf16 v[50:65], v[152:155], v[98:101], v[50:65]
	ds_read_b64_tr_b16 v[94:95], v236 offset:17600
	ds_read_b64_tr_b16 v[96:97], v236 offset:20160
	s_waitcnt lgkmcnt(14)
	v_mfma_f32_32x32x16_bf16 v[34:49], v[156:159], v[102:105], v[34:49]
	ds_read_b64_tr_b16 v[106:107], v236 offset:22656
	ds_read_b64_tr_b16 v[108:109], v236 offset:25216
	s_waitcnt lgkmcnt(14)
	v_mfma_f32_32x32x16_bf16 v[50:65], v[160:163], v[102:105], v[50:65]
	ds_read_b64_tr_b16 v[110:111], v236 offset:22720
	ds_read_b64_tr_b16 v[112:113], v236 offset:25280
	s_waitcnt lgkmcnt(14)
	v_mfma_f32_32x32x16_bf16 v[34:49], v[164:167], v[82:85], v[34:49]
	ds_read_b64_tr_b16 v[240:241], v236 offset:27776
	ds_read_b64_tr_b16 v[242:243], v236 offset:30336
	s_waitcnt lgkmcnt(14)
	v_mfma_f32_32x32x16_bf16 v[50:65], v[168:171], v[82:85], v[50:65]
	ds_read_b64_tr_b16 v[148:149], v236 offset:27840
	ds_read_b64_tr_b16 v[150:151], v236 offset:30400
	s_waitcnt lgkmcnt(14)
	v_mfma_f32_32x32x16_bf16 v[50:65], v[172:175], v[86:89], v[50:65]
	ds_read_b64_tr_b16 v[152:153], v236 offset:32896
	ds_read_b64_tr_b16 v[154:155], v236 offset:35456
	s_waitcnt lgkmcnt(14)
	v_mfma_f32_32x32x16_bf16 v[34:49], v[176:179], v[86:89], v[34:49]
	ds_read_b64_tr_b16 v[156:157], v236 offset:32960
	ds_read_b64_tr_b16 v[158:159], v236 offset:35520
	s_waitcnt lgkmcnt(14)
	v_mfma_f32_32x32x16_bf16 v[18:33], v[90:93], v[98:101], v[18:33]
	ds_read_b128 v[160:163], v239
	s_waitcnt lgkmcnt(13)
	v_mfma_f32_32x32x16_bf16 v[2:17], v[94:97], v[98:101], v[2:17]
	ds_read_b128 v[164:167], v239 offset:8704
	s_waitcnt lgkmcnt(12)
	v_mfma_f32_32x32x16_bf16 v[18:33], v[106:109], v[102:105], v[18:33]
	ds_read_b128 v[168:171], v239 offset:32
	s_waitcnt lgkmcnt(11)
	v_mfma_f32_32x32x16_bf16 v[2:17], v[110:113], v[102:105], v[2:17]
	ds_read_b128 v[172:175], v239 offset:8736
	s_waitcnt lgkmcnt(10)
	v_mfma_f32_32x32x16_bf16 v[18:33], v[240:243], v[82:85], v[18:33]
	ds_read_b128 v[176:179], v239 offset:64
	s_waitcnt lgkmcnt(9)
	v_mfma_f32_32x32x16_bf16 v[2:17], v[148:151], v[82:85], v[2:17]
	ds_read_b128 v[240:243], v239 offset:8768
	s_waitcnt lgkmcnt(8)
	v_mfma_f32_32x32x16_bf16 v[18:33], v[152:155], v[86:89], v[18:33]
	ds_read_b128 v[148:151], v239 offset:96
	s_waitcnt lgkmcnt(7)
	v_mfma_f32_32x32x16_bf16 v[2:17], v[156:159], v[86:89], v[2:17]
	ds_read_b128 v[152:155], v239 offset:8800
	s_waitcnt lgkmcnt(7)
	v_mfma_f32_32x32x16_bf16 v[98:113], v[160:163], v[116:119], v[66:81]
	s_waitcnt lgkmcnt(6)
	v_mfma_f32_32x32x16_bf16 v[82:97], v[164:167], v[116:119], v[66:81]
	s_waitcnt lgkmcnt(5)
	v_mfma_f32_32x32x16_bf16 v[98:113], v[168:171], v[120:123], v[98:113]
	s_waitcnt lgkmcnt(4)
	v_mfma_f32_32x32x16_bf16 v[82:97], v[172:175], v[120:123], v[82:97]
	s_waitcnt lgkmcnt(3)
	v_mfma_f32_32x32x16_bf16 v[98:113], v[176:179], v[124:127], v[98:113]
	s_waitcnt lgkmcnt(2)
	v_mfma_f32_32x32x16_bf16 v[82:97], v[240:243], v[124:127], v[82:97]
	s_waitcnt lgkmcnt(1)
	v_mfma_f32_32x32x16_bf16 v[98:113], v[148:151], v[128:131], v[98:113]
	s_waitcnt lgkmcnt(0)
	v_mfma_f32_32x32x16_bf16 v[82:97], v[152:155], v[128:131], v[82:97]

; template <bool DIFF>
; __device__ __forceinline__ void attn_unit(const AttnP& A, int b, int h, int qi, ldsp lds) {
;     ...
;         if (kt + 1 < nt) LOAD_TILE(kt + 1);
;         if (64 * kt <= qmax_w) {
;             ldsp Kb = lds + (kt & 1) * STAGE; ldsp Vb = Kb + 64 * KP;
;             bf16x8 kf[8]; bf16x8 ka0, ka1, qa; f32x16 s0, s1;
.Lda1_snov:
	s_cmp_ge_i32 s75, s31
	s_cbranch_scc1 .Lda3_nold
	global_load_dwordx4 v[136:139], v[196:197], off offset:2048
	global_load_dwordx4 v[144:147], v[198:199], off offset:2048
	v_lshl_add_u64 v[196:197], v[196:197], 0, s[26:27]
	v_lshl_add_u64 v[198:199], v[198:199], 0, s[26:27]
	global_load_dwordx4 v[132:135], v[196:197], off offset:1024
	global_load_dwordx4 v[140:143], v[198:199], off offset:1024

; __device__ __forceinline__ s16x4 vtr(ldsp p) { return __builtin_bit_cast(s16x4, __builtin_amdgcn_ds_read_tr16_b64_v4i16((LAS v4i16_t*)p)); }
; #define MASK_BLOCK() do { if (kt == 0 || kt >= diag0) { \
;             _Pragma("unroll") for (int r = 0; r < 16; ++r) { const int kpp = 64 * kt + crow(r, hi); \
;                 if (kpp < 48 || kpp > q_pp) s0[r] = -INFINITY; \
;                 if (kpp + 32 < 48 || kpp + 32 > q_pp) s1[r] = -INFINITY; } } } while (0)
; #define EXPSUM_BLOCK() do { psa = 0.f; psb = 0.f; \
;             _Pragma("unroll") for (int r = 0; r < 16; ++r) { s0[r] = __builtin_amdgcn_exp2f(s0[r]); s1[r] = __builtin_amdgcn_exp2f(s1[r]); psa += s0[r]; asm("" : "+v"(psa)); psb += s1[r]; asm("" : "+v"(psb)); } } while (0)
; template <bool DIFF>
; __device__ __forceinline__ void attn_unit(const AttnP& A, int b, int h, int qi, ldsp lds) {
;     ...
;             QK_BLOCK();
;             s16x4 vlo[8], vhi[8];
; #pragma unroll
;             for (int t = 0; t < 2; ++t)
; #pragma unroll
;                 for (int j = 0; j < 4; ++j) { vlo[t * 4 + j] = vtr(Vb + trb + (16 * j) * VP + t * 64); vhi[t * 4 + j] = vtr(Vb + trb + (16 * j + 8) * VP + t * 64); }
;             __builtin_amdgcn_sched_barrier(0);
;             MASK_BLOCK();
;             bool full = (kt == kt0);
;             float psa, psb;
;             if (!full) {
;                 EXPSUM_BLOCK();
;                 if (__any(psa + psb > 1.0e18f)) { full = true; QK_BLOCK();
; #pragma unroll
;                     for (int t = 0; t < 2; ++t)
; #pragma unroll
;                         for (int j = 0; j < 4; ++j) { vlo[t * 4 + j] = vtr(Vb + trb + (16 * j) * VP + t * 64); vhi[t * 4 + j] = vtr(Vb + trb + (16 * j + 8) * VP + t * 64); }
;                     MASK_BLOCK(); }
;             }
.Ldb_top:
	s_bitcmp1_b32 s75, 0
	s_cselect_b32 s45, 0x9500, 0
	s_sub_i32 s71, 0x9500, s45
	s_cmp_eq_u32 s75, 0
	s_cbranch_scc1 .Ldb_first
	s_cmp_gt_i32 s75, s44
	s_cbranch_scc1 .Ldb_stores
	s_add_i32 s73, s74, -64
	s_cmp_eq_u32 s73, 0
	s_cselect_b64 s[40:41], -1, 0
	s_cselect_b64 s[48:49], 0, -1
	s_lshr_b32 s0, s73, 6
	s_cmp_ge_i32 s0, s72
	s_cselect_b64 s[46:47], -1, 0
	s_or_b64 s[46:47], s[46:47], s[40:41]
	s_or_b64 s[46:47], s[46:47], s[24:25]
	s_and_b64 vcc, exec, s[46:47]
	s_cbranch_vccz .Lda10_nomask
	v_add_u32_e32 v204, s73, v115
	v_cmp_gt_i32_e32 vcc, v204, v192
	s_or_b64 vcc, s[40:41], vcc
	v_add_u32_e32 v205, 32, v204
	v_cndmask_b32_e32 v98, v98, v223, vcc
	v_cmp_gt_i32_e32 vcc, v205, v192
	s_or_b64 vcc, s[40:41], vcc
	v_add_u32_e32 v205, 33, v204
	v_cndmask_b32_e32 v82, v82, v223, vcc
	v_cmp_ge_i32_e32 vcc, v204, v192
	s_or_b64 vcc, s[40:41], vcc
	s_nop 0
	v_cndmask_b32_e32 v99, v99, v223, vcc
	v_cmp_gt_i32_e32 vcc, v205, v192
	s_or_b64 vcc, s[40:41], vcc
	v_add_u32_e32 v205, 2, v204
	v_cndmask_b32_e32 v83, v83, v223, vcc
	v_cmp_gt_i32_e32 vcc, v205, v192
	s_or_b64 vcc, s[40:41], vcc
	v_add_u32_e32 v205, 34, v204
	v_cndmask_b32_e32 v100, v100, v223, vcc
	v_cmp_gt_i32_e32 vcc, v205, v192
	s_or_b64 vcc, s[40:41], vcc
	v_add_u32_e32 v205, 3, v204
	v_cndmask_b32_e32 v84, v84, v223, vcc
	v_cmp_gt_i32_e32 vcc, v205, v192
	s_or_b64 vcc, s[40:41], vcc
	v_add_u32_e32 v205, 35, v204
	v_cndmask_b32_e32 v101, v101, v223, vcc
	v_cmp_gt_i32_e32 vcc, v205, v192
	s_or_b64 vcc, s[40:41], vcc
	v_add_u32_e32 v205, 8, v204
	v_cndmask_b32_e32 v85, v85, v223, vcc
	v_cmp_gt_i32_e32 vcc, v205, v192
	s_or_b64 vcc, s[40:41], vcc
	v_add_u32_e32 v205, 40, v204
	v_cndmask_b32_e32 v102, v102, v223, vcc
	v_cmp_gt_i32_e32 vcc, v205, v192
	s_or_b64 vcc, s[40:41], vcc
	v_add_u32_e32 v205, 9, v204
	v_cndmask_b32_e32 v86, v86, v223, vcc
	v_cmp_gt_i32_e32 vcc, v205, v192
	s_or_b64 vcc, s[40:41], vcc
	v_add_u32_e32 v205, 41, v204
	v_cndmask_b32_e32 v103, v103, v223, vcc
	v_cmp_gt_i32_e32 vcc, v205, v192
	s_or_b64 vcc, s[40:41], vcc
	v_add_u32_e32 v205, 10, v204
	v_cndmask_b32_e32 v87, v87, v223, vcc
	v_cmp_gt_i32_e32 vcc, v205, v192
	s_or_b64 vcc, s[40:41], vcc
	v_add_u32_e32 v205, 42, v204
	v_cndmask_b32_e32 v104, v104, v223, vcc
	v_cmp_gt_i32_e32 vcc, v205, v192
	s_or_b64 vcc, s[40:41], vcc
	v_add_u32_e32 v205, 11, v204
	v_cndmask_b32_e32 v88, v88, v223, vcc
	v_cmp_gt_i32_e32 vcc, v205, v192
	s_or_b64 vcc, s[40:41], vcc
	v_add_u32_e32 v205, 43, v204
	v_cndmask_b32_e32 v105, v105, v223, vcc
	v_cmp_gt_i32_e32 vcc, v205, v192
	s_or_b64 vcc, s[40:41], vcc
	v_add_u32_e32 v205, 16, v204
	v_cndmask_b32_e32 v89, v89, v223, vcc
	v_cmp_gt_u32_e32 vcc, 48, v205
	v_cmp_gt_i32_e64 s[46:47], v205, v192
	s_or_b64 vcc, vcc, s[46:47]
	v_add_u32_e32 v205, 48, v204
	v_cndmask_b32_e32 v106, v106, v223, vcc
	v_cmp_le_i32_e32 vcc, v205, v192
	v_add_u32_e32 v205, 17, v204
	v_cmp_gt_i32_e64 s[46:47], v205, v192
	v_cndmask_b32_e32 v90, v223, v90, vcc
	v_cmp_gt_u32_e32 vcc, 48, v205
	s_or_b64 vcc, vcc, s[46:47]
	v_add_u32_e32 v205, 49, v204
	v_cndmask_b32_e32 v107, v107, v223, vcc
	v_cmp_le_i32_e32 vcc, v205, v192
	v_add_u32_e32 v205, 18, v204
	v_cmp_gt_i32_e64 s[46:47], v205, v192
	v_cndmask_b32_e32 v91, v223, v91, vcc
	v_cmp_gt_u32_e32 vcc, 48, v205
	s_or_b64 vcc, vcc, s[46:47]
	v_add_u32_e32 v205, 50, v204
	v_cndmask_b32_e32 v108, v108, v223, vcc
	v_cmp_le_i32_e32 vcc, v205, v192
	v_add_u32_e32 v205, 19, v204
	v_cmp_gt_i32_e64 s[46:47], v205, v192
	v_cndmask_b32_e32 v92, v223, v92, vcc
	v_cmp_gt_u32_e32 vcc, 48, v205
	s_or_b64 vcc, vcc, s[46:47]
	v_add_u32_e32 v205, 51, v204
	v_cndmask_b32_e32 v109, v109, v223, vcc
	v_cmp_le_i32_e32 vcc, v205, v192
	v_add_u32_e32 v205, 24, v204
	v_cmp_gt_i32_e64 s[46:47], v205, v192
	v_cndmask_b32_e32 v93, v223, v93, vcc
	v_cmp_gt_u32_e32 vcc, 48, v205
	s_or_b64 vcc, vcc, s[46:47]
	v_add_u32_e32 v205, 56, v204
	v_cndmask_b32_e32 v110, v110, v223, vcc
	v_cmp_le_i32_e32 vcc, v205, v192
	v_add_u32_e32 v205, 25, v204
	v_cmp_gt_i32_e64 s[46:47], v205, v192
	v_cndmask_b32_e32 v94, v223, v94, vcc
	v_cmp_gt_u32_e32 vcc, 48, v205
	s_or_b64 vcc, vcc, s[46:47]
	v_add_u32_e32 v205, 57, v204
	v_cndmask_b32_e32 v111, v111, v223, vcc
	v_cmp_le_i32_e32 vcc, v205, v192
	v_add_u32_e32 v205, 26, v204
	v_cmp_gt_i32_e64 s[46:47], v205, v192
	v_cndmask_b32_e32 v95, v223, v95, vcc
	v_cmp_gt_u32_e32 vcc, 48, v205
	s_or_b64 vcc, vcc, s[46:47]
	v_add_u32_e32 v205, 58, v204
	v_cndmask_b32_e32 v112, v112, v223, vcc
	v_cmp_le_i32_e32 vcc, v205, v192
	v_add_u32_e32 v205, 27, v204
	v_cmp_gt_i32_e64 s[46:47], v205, v192
	v_cndmask_b32_e32 v96, v223, v96, vcc
	v_cmp_gt_u32_e32 vcc, 48, v205
	s_or_b64 vcc, vcc, s[46:47]
	v_add_u32_e32 v204, 59, v204
	v_cndmask_b32_e32 v113, v113, v223, vcc
	v_cmp_le_i32_e32 vcc, v204, v192
	s_nop 1
	v_cndmask_b32_e32 v97, v223, v97, vcc

; __device__ __forceinline__ unsigned cvtpk(float lo, float hi) { f32x2 v = {lo, hi}; bf16x2_t b = __builtin_convertvector(v, bf16x2_t); return __builtin_bit_cast(unsigned, b); }
; __device__ __forceinline__ s16x4 vtr(ldsp p) { return __builtin_bit_cast(s16x4, __builtin_amdgcn_ds_read_tr16_b64_v4i16((LAS v4i16_t*)p)); }
; template <bool DIFF>
; __device__ __forceinline__ void attn_unit(const AttnP& A, int b, int h, int qi, ldsp lds) {
;     ...
;             bf16x8 pw[4];
; #pragma unroll
;             for (int j = 0; j < 4; ++j) {
;                 u32x4 pk;
;                 if (j < 2) { const int rb = 8 * (j & 1); pk.x = cvtpk(s0[rb], s0[rb + 1]); pk.y = cvtpk(s0[rb + 2], s0[rb + 3]); pk.z = cvtpk(s0[rb + 4], s0[rb + 5]); pk.w = cvtpk(s0[rb + 6], s0[rb + 7]); }
;                 else { const int rb = 8 * (j & 1); pk.x = cvtpk(s1[rb], s1[rb + 1]); pk.y = cvtpk(s1[rb + 2], s1[rb + 3]); pk.z = cvtpk(s1[rb + 4], s1[rb + 5]); pk.w = cvtpk(s1[rb + 6], s1[rb + 7]); }
;                 pw[j] = __builtin_bit_cast(bf16x8, pk);
;             }
;             __builtin_amdgcn_sched_barrier(0);
;             __builtin_amdgcn_s_setprio(1);
; #pragma unroll
;             for (int t = 0; t < 2; ++t)
; #pragma unroll
;                 for (int j = 0; j < 4; ++j) {
;                     const bf16x8 vf = (bf16x8){vlo[t * 4 + j][0], vlo[t * 4 + j][1], vlo[t * 4 + j][2], vlo[t * 4 + j][3], vhi[t * 4 + j][0], vhi[t * 4 + j][1], vhi[t * 4 + j][2], vhi[t * 4 + j][3]};
;                     o[t] = __builtin_amdgcn_mfma_f32_32x32x16_bf16(vf, pw[j], o[t], 0, 0, 0);
;                 }
;             if (DIFF) {
; #pragma unroll
;                 for (int t = 2; t < NTD; ++t)
; #pragma unroll
;                     for (int j = 0; j < 4; ++j) { vlo[(t - 2) * 4 + j] = vtr(Vb + trb + (16 * j) * VP + t * 64); vhi[(t - 2) * 4 + j] = vtr(Vb + trb + (16 * j + 8) * VP + t * 64); }
;                 __builtin_amdgcn_sched_barrier(0);
; #pragma unroll
;                 for (int t = 2; t < NTD; ++t)
; #pragma unroll
;                     for (int j = 0; j < 4; ++j) {
;                         const int i = (t - 2) * 4 + j;
;                         const bf16x8 vf = (bf16x8){vlo[i][0], vlo[i][1], vlo[i][2], vlo[i][3], vhi[i][0], vhi[i][1], vhi[i][2], vhi[i][3]};
;                         o[t] = __builtin_amdgcn_mfma_f32_32x32x16_bf16(vf, pw[j], o[t], 0, 0, 0);
;                     }
;             }
.Lda12_pack:
	v_add_u32_e32 v239, s45, v234
	v_add_u32_e32 v236, s71, v231
	ds_read_b64_tr_b16 v[90:91], v236 offset:17472
	ds_read_b64_tr_b16 v[92:93], v236 offset:20032
	ds_read_b64_tr_b16 v[94:95], v236 offset:17408
	ds_read_b64_tr_b16 v[96:97], v236 offset:19968
	ds_read_b64_tr_b16 v[106:107], v236 offset:22592
	ds_read_b64_tr_b16 v[108:109], v236 offset:25152
	ds_read_b64_tr_b16 v[110:111], v236 offset:22528
	ds_read_b64_tr_b16 v[112:113], v236 offset:25088
	ds_read_b64_tr_b16 v[240:241], v236 offset:27712
	ds_read_b64_tr_b16 v[242:243], v236 offset:30272
	v_add_f32_e32 v204, v238, v237
	v_cvt_pk_bf16_f32 v98, v148, v149
	v_cvt_pk_bf16_f32 v99, v150, v151
	v_cvt_pk_bf16_f32 v100, v152, v153
	v_cvt_pk_bf16_f32 v101, v154, v155
	v_cvt_pk_bf16_f32 v102, v156, v157
	v_cvt_pk_bf16_f32 v103, v158, v159
	v_cvt_pk_bf16_f32 v104, v160, v161
	v_cvt_pk_bf16_f32 v105, v162, v163
	v_cvt_pk_bf16_f32 v82, v164, v165
	v_cvt_pk_bf16_f32 v83, v166, v167
	v_cvt_pk_bf16_f32 v84, v168, v169
	v_cvt_pk_bf16_f32 v85, v170, v171
	v_cvt_pk_bf16_f32 v86, v172, v173
	v_cvt_pk_bf16_f32 v87, v174, v175
	v_cvt_pk_bf16_f32 v88, v176, v177
	v_cvt_pk_bf16_f32 v89, v178, v179
	v_add_f32_e32 v230, v204, v230
	ds_read_b64_tr_b16 v[148:149], v236 offset:27648
	ds_read_b64_tr_b16 v[150:151], v236 offset:30208
	ds_read_b64_tr_b16 v[152:153], v236 offset:32768
	ds_read_b64_tr_b16 v[154:155], v236 offset:35328
	ds_read_b64_tr_b16 v[156:157], v236 offset:32832
	ds_read_b64_tr_b16 v[158:159], v236 offset:35392
	s_cmp_eq_u32 s75, s44
	s_cbranch_scc1 .Ldb_last
	s_setprio 1
	s_waitcnt lgkmcnt(14)
	v_mfma_f32_32x32x16_bf16 v[34:49], v[90:93], v[98:101], v[34:49]
	ds_read_b64_tr_b16 v[160:161], v236 offset:17536
	ds_read_b64_tr_b16 v[162:163], v236 offset:20096
	s_waitcnt lgkmcnt(14)
	v_mfma_f32_32x32x16_bf16 v[50:65], v[94:97], v[98:101], v[50:65]
	ds_read_b64_tr_b16 v[164:165], v236 offset:17600
	ds_read_b64_tr_b16 v[166:167], v236 offset:20160
	s_waitcnt lgkmcnt(14)
	v_mfma_f32_32x32x16_bf16 v[34:49], v[106:109], v[102:105], v[34:49]
	ds_read_b64_tr_b16 v[168:169], v236 offset:22656
	ds_read_b64_tr_b16 v[170:171], v236 offset:25216
	s_waitcnt lgkmcnt(14)
	v_mfma_f32_32x32x16_bf16 v[50:65], v[110:113], v[102:105], v[50:65]
	ds_read_b64_tr_b16 v[172:173], v236 offset:22720
	ds_read_b64_tr_b16 v[174:175], v236 offset:25280
	s_waitcnt lgkmcnt(14)
	v_mfma_f32_32x32x16_bf16 v[34:49], v[240:243], v[82:85], v[34:49]
	ds_read_b64_tr_b16 v[176:177], v236 offset:27776
	ds_read_b64_tr_b16 v[178:179], v236 offset:30336
	s_waitcnt lgkmcnt(14)
	v_mfma_f32_32x32x16_bf16 v[50:65], v[148:151], v[82:85], v[50:65]
	ds_read_b64_tr_b16 v[90:91], v236 offset:27840
	ds_read_b64_tr_b16 v[92:93], v236 offset:30400
	s_waitcnt lgkmcnt(14)
	v_mfma_f32_32x32x16_bf16 v[50:65], v[152:155], v[86:89], v[50:65]
	ds_read_b64_tr_b16 v[94:95], v236 offset:32896
	ds_read_b64_tr_b16 v[96:97], v236 offset:35456
	s_waitcnt lgkmcnt(14)
	v_mfma_f32_32x32x16_bf16 v[34:49], v[156:159], v[86:89], v[34:49]
	ds_read_b64_tr_b16 v[106:107], v236 offset:32960
	ds_read_b64_tr_b16 v[108:109], v236 offset:35520
	s_waitcnt lgkmcnt(14)
	v_mfma_f32_32x32x16_bf16 v[18:33], v[160:163], v[98:101], v[18:33]
	ds_read_b128 v[240:243], v239
	s_waitcnt lgkmcnt(13)
	v_mfma_f32_32x32x16_bf16 v[2:17], v[164:167], v[98:101], v[2:17]
	ds_read_b128 v[148:151], v239 offset:8704
	s_waitcnt lgkmcnt(12)
	v_mfma_f32_32x32x16_bf16 v[18:33], v[168:171], v[102:105], v[18:33]
	ds_read_b128 v[152:155], v239 offset:32
	s_waitcnt lgkmcnt(11)
	v_mfma_f32_32x32x16_bf16 v[2:17], v[172:175], v[102:105], v[2:17]
	ds_read_b128 v[156:159], v239 offset:8736
	s_waitcnt lgkmcnt(10)
	v_mfma_f32_32x32x16_bf16 v[18:33], v[176:179], v[82:85], v[18:33]
	ds_read_b128 v[160:163], v239 offset:64
	s_waitcnt lgkmcnt(9)
	v_mfma_f32_32x32x16_bf16 v[2:17], v[90:93], v[82:85], v[2:17]
	ds_read_b128 v[164:167], v239 offset:8768
	s_waitcnt lgkmcnt(8)
	v_mfma_f32_32x32x16_bf16 v[18:33], v[94:97], v[86:89], v[18:33]
	ds_read_b128 v[168:171], v239 offset:96
	s_waitcnt lgkmcnt(7)
	v_mfma_f32_32x32x16_bf16 v[2:17], v[106:109], v[86:89], v[2:17]
	ds_read_b128 v[172:175], v239 offset:8800
	s_waitcnt lgkmcnt(7)
	v_mfma_f32_32x32x16_bf16 v[98:113], v[240:243], v[116:119], v[66:81]
	s_waitcnt lgkmcnt(6)
	v_mfma_f32_32x32x16_bf16 v[82:97], v[148:151], v[116:119], v[66:81]
	s_waitcnt lgkmcnt(5)
	v_mfma_f32_32x32x16_bf16 v[98:113], v[152:155], v[120:123], v[98:113]
	s_waitcnt lgkmcnt(4)
	v_mfma_f32_32x32x16_bf16 v[82:97], v[156:159], v[120:123], v[82:97]
	s_waitcnt lgkmcnt(3)
	v_mfma_f32_32x32x16_bf16 v[98:113], v[160:163], v[124:127], v[98:113]
	s_waitcnt lgkmcnt(2)
	v_mfma_f32_32x32x16_bf16 v[82:97], v[164:167], v[124:127], v[82:97]
	s_waitcnt lgkmcnt(1)
	v_mfma_f32_32x32x16_bf16 v[98:113], v[168:171], v[128:131], v[98:113]
	s_waitcnt lgkmcnt(0)
	v_mfma_f32_32x32x16_bf16 v[82:97], v[172:175], v[128:131], v[82:97]
	s_setprio 0
	s_branch .Ldb_stores
; __device__ __forceinline__ s16x4 vtr(ldsp p) { return __builtin_bit_cast(s16x4, __builtin_amdgcn_ds_read_tr16_b64_v4i16((LAS v4i16_t*)p)); }
; template <bool DIFF>
; __device__ __forceinline__ void attn_unit(const AttnP& A, int b, int h, int qi, ldsp lds) {
;     ...
; #pragma unroll
;             for (int t = 0; t < 2; ++t)
; #pragma unroll
;                 for (int j = 0; j < 4; ++j) {
;                     const bf16x8 vf = (bf16x8){vlo[t * 4 + j][0], vlo[t * 4 + j][1], vlo[t * 4 + j][2], vlo[t * 4 + j][3], vhi[t * 4 + j][0], vhi[t * 4 + j][1], vhi[t * 4 + j][2], vhi[t * 4 + j][3]};
;                     o[t] = __builtin_amdgcn_mfma_f32_32x32x16_bf16(vf, pw[j], o[t], 0, 0, 0);
;                 }
;             if (DIFF) {
; #pragma unroll
;                 for (int t = 2; t < NTD; ++t)
; #pragma unroll
;                     for (int j = 0; j < 4; ++j) { vlo[(t - 2) * 4 + j] = vtr(Vb + trb + (16 * j) * VP + t * 64); vhi[(t - 2) * 4 + j] = vtr(Vb + trb + (16 * j + 8) * VP + t * 64); }
;                 __builtin_amdgcn_sched_barrier(0);
; #pragma unroll
;                 for (int t = 2; t < NTD; ++t)
; #pragma unroll
;                     for (int j = 0; j < 4; ++j) {
;                         const int i = (t - 2) * 4 + j;
;                         const bf16x8 vf = (bf16x8){vlo[i][0], vlo[i][1], vlo[i][2], vlo[i][3], vhi[i][0], vhi[i][1], vhi[i][2], vhi[i][3]};
;                         o[t] = __builtin_amdgcn_mfma_f32_32x32x16_bf16(vf, pw[j], o[t], 0, 0, 0);
;                     }
;             }
.Ldb_last:
	s_setprio 1
	s_waitcnt lgkmcnt(14)
	v_mfma_f32_32x32x16_bf16 v[34:49], v[90:93], v[98:101], v[34:49]
	ds_read_b64_tr_b16 v[160:161], v236 offset:17536
	ds_read_b64_tr_b16 v[162:163], v236 offset:20096
	s_waitcnt lgkmcnt(14)
	v_mfma_f32_32x32x16_bf16 v[50:65], v[94:97], v[98:101], v[50:65]
	ds_read_b64_tr_b16 v[164:165], v236 offset:17600
	ds_read_b64_tr_b16 v[166:167], v236 offset:20160
	s_waitcnt lgkmcnt(14)
	v_mfma_f32_32x32x16_bf16 v[34:49], v[106:109], v[102:105], v[34:49]
	ds_read_b64_tr_b16 v[168:169], v236 offset:22656
	ds_read_b64_tr_b16 v[170:171], v236 offset:25216
	s_waitcnt lgkmcnt(14)
	v_mfma_f32_32x32x16_bf16 v[50:65], v[110:113], v[102:105], v[50:65]
	ds_read_b64_tr_b16 v[172:173], v236 offset:22720
	ds_read_b64_tr_b16 v[174:175], v236 offset:25280
	s_waitcnt lgkmcnt(14)
	v_mfma_f32_32x32x16_bf16 v[34:49], v[240:243], v[82:85], v[34:49]
	ds_read_b64_tr_b16 v[176:177], v236 offset:27776
	ds_read_b64_tr_b16 v[178:179], v236 offset:30336
	s_waitcnt lgkmcnt(14)
	v_mfma_f32_32x32x16_bf16 v[50:65], v[148:151], v[82:85], v[50:65]
	ds_read_b64_tr_b16 v[90:91], v236 offset:27840
	ds_read_b64_tr_b16 v[92:93], v236 offset:30400
	s_waitcnt lgkmcnt(14)
	v_mfma_f32_32x32x16_bf16 v[50:65], v[152:155], v[86:89], v[50:65]
	ds_read_b64_tr_b16 v[94:95], v236 offset:32896
	ds_read_b64_tr_b16 v[96:97], v236 offset:35456
	s_waitcnt lgkmcnt(14)
	v_mfma_f32_32x32x16_bf16 v[34:49], v[156:159], v[86:89], v[34:49]
	ds_read_b64_tr_b16 v[106:107], v236 offset:32960
	ds_read_b64_tr_b16 v[108:109], v236 offset:35520
	s_waitcnt lgkmcnt(14)
	v_mfma_f32_32x32x16_bf16 v[18:33], v[160:163], v[98:101], v[18:33]
	s_waitcnt lgkmcnt(12)
	v_mfma_f32_32x32x16_bf16 v[2:17], v[164:167], v[98:101], v[2:17]
	s_waitcnt lgkmcnt(10)
	v_mfma_f32_32x32x16_bf16 v[18:33], v[168:171], v[102:105], v[18:33]
	s_waitcnt lgkmcnt(8)
	v_mfma_f32_32x32x16_bf16 v[2:17], v[172:175], v[102:105], v[2:17]
	s_waitcnt lgkmcnt(6)
	v_mfma_f32_32x32x16_bf16 v[18:33], v[176:179], v[82:85], v[18:33]
	s_waitcnt lgkmcnt(4)
	v_mfma_f32_32x32x16_bf16 v[2:17], v[90:93], v[82:85], v[2:17]
	s_waitcnt lgkmcnt(2)
	v_mfma_f32_32x32x16_bf16 v[18:33], v[94:97], v[86:89], v[18:33]
	s_waitcnt lgkmcnt(0)
	v_mfma_f32_32x32x16_bf16 v[2:17], v[106:109], v[86:89], v[2:17]
	s_setprio 0
	s_branch .Ldb_stores
.Ldb_first:
	v_add_u32_e32 v239, s45, v234
	ds_read_b128 v[148:151], v239
	ds_read_b128 v[152:155], v239 offset:8704
	ds_read_b128 v[156:159], v239 offset:32
	ds_read_b128 v[160:163], v239 offset:8736
	ds_read_b128 v[164:167], v239 offset:64
	ds_read_b128 v[168:171], v239 offset:8768
	ds_read_b128 v[172:175], v239 offset:96
	ds_read_b128 v[176:179], v239 offset:8800
	s_setprio 1
	s_waitcnt lgkmcnt(7)
	v_mfma_f32_32x32x16_bf16 v[98:113], v[148:151], v[116:119], v[66:81]
	s_waitcnt lgkmcnt(6)
	v_mfma_f32_32x32x16_bf16 v[82:97], v[152:155], v[116:119], v[66:81]
	s_waitcnt lgkmcnt(5)
	v_mfma_f32_32x32x16_bf16 v[98:113], v[156:159], v[120:123], v[98:113]
	s_waitcnt lgkmcnt(4)
	v_mfma_f32_32x32x16_bf16 v[82:97], v[160:163], v[120:123], v[82:97]
	s_waitcnt lgkmcnt(3)
	v_mfma_f32_32x32x16_bf16 v[98:113], v[164:167], v[124:127], v[98:113]
	s_waitcnt lgkmcnt(2)
	v_mfma_f32_32x32x16_bf16 v[82:97], v[168:171], v[124:127], v[82:97]
	s_waitcnt lgkmcnt(1)
	v_mfma_f32_32x32x16_bf16 v[98:113], v[172:175], v[128:131], v[98:113]
	s_waitcnt lgkmcnt(0)
	v_mfma_f32_32x32x16_bf16 v[82:97], v[176:179], v[128:131], v[82:97]
	s_setprio 0
